# ret_out: q-rope table loads and the second decay exponent issued before the next item's prefetch (no wait behind the 96 KB prefetch)
# speedup vs baseline: 1.0071x; 1.0071x over previous
; #define LAS __attribute__((address_space(3)))
; DEVI void ph_ret_out(const int wv, const Params& p, int l, unsigned char* lds_raw) {
;     ...
;         const int bh = it / nch, ci = it - bh * nch, b = bh >> 2, h = bh & 3, cid = l == 0 ? ci : ci + 2;
;         const int row0 = cid < 2 ? NLAT + b * 256 + cid * 128 : b * 2048 + (cid - 2) * 128;
;         const float lgf = log1pf(-exp2f(-p.in[9][(l * 2 + 0) * 4 + h])) * 1.4426950408889634f, lgb = log1pf(-exp2f(-p.in[9][(l * 2 + 1) * 4 + h])) * 1.4426950408889634f;
;         __syncthreads();
; #pragma unroll
;         for (int rep = 0; rep < 2; ++rep) { const int pi = tid + 512 * rep, r = pi >> 3, g8 = pi & 7;
;             *(LAS u32x4*)(Kl + r * 144 + g8 * 16) = pk[rep]; *(LAS u32x4*)(Ql + r * 144 + g8 * 16) = pq[rep]; }
; #pragma unroll
;         for (int rep = 0; rep < 4; ++rep) { const int pi = tid + 512 * rep;
;             *(LAS u32x4*)(Rl + (pi >> 4) * 272 + (pi & 15) * 16) = pr[rep];
;             *(LAS u32x4*)(Vt + (pi >> 4) * 288 + (pi & 15) * 16) = pvv[rep]; }
;         __syncthreads();
;         if (it + (int)gridDim.x < nitems) RO_LOAD(it + (int)gridDim.x);
;     ...
;             const float* cp = (const float*)(p.ws + OFF_RT) + (size_t)(((row0 + ii) & 2047) * 32 + fq * 8) * 2;
.LBB0_737:
	s_and_b32 s29, s18, 3
	s_or_b32 s18, s29, s41
	s_lshl_b64 s[10:11], s[18:19], 2
	s_add_u32 s10, s78, s10
	s_addc_u32 s11, s79, s11
	global_load_dword v50, v1, s[10:11]
	global_load_dword v255, v1, s[10:11] offset:16
	s_mov_b32 s38, 0x42fc0000
	s_waitcnt vmcnt(0)
	v_cmp_lt_f32_e32 vcc, s38, v50
	s_nop 1
	v_cndmask_b32_e32 v51, 0, v234, vcc
	v_sub_f32_e32 v50, v51, v50
	v_exp_f32_e32 v50, v50
	s_and_b64 s[36:37], vcc, exec
	s_cselect_b32 s18, 0xffffffc0, 0
	v_ldexp_f32 v62, v50, s18
	v_sub_f32_e32 v51, 1.0, v62
	v_frexp_mant_f32_e32 v50, v51
	s_mov_b32 s18, 0x3f2aaaab
	v_cmp_gt_f32_e64 s[72:73], s18, v50
	v_mov_b32_e32 v50, v255
	v_add_u32_e32 v254, s30, v91
	v_lshlrev_b32_e32 v254, 6, v254
	s_mov_b32 s36, 0x1ffc0
	v_and_or_b32 v254, v254, s36, v95
	v_readlane_b32 s100, v252, 17
	v_lshlrev_b32_e32 v254, 2, v254
	v_readlane_b32 s101, v252, 18
	s_nop 4
	global_load_dwordx4 v[116:119], v254, s[100:101] offset:48
	global_load_dwordx4 v[104:107], v254, s[100:101] offset:32
	global_load_dwordx4 v[108:111], v254, s[100:101] offset:16
	global_load_dwordx4 v[112:115], v254, s[100:101]
	s_barrier
	ds_write_b128 v190, v[38:41]
	ds_write_b128 v190, v[42:45] offset:18432
	ds_write_b128 v191, v[30:33]
	ds_write_b128 v191, v[34:37] offset:18432
	ds_write_b128 v192, v[46:49]
	ds_write_b128 v193, v[22:25] offset:36864
	ds_write_b128 v194, v[26:29]
	ds_write_b128 v195, v[18:21] offset:36864
	ds_write_b128 v199, v[14:17]
	ds_write_b128 v200, v[10:13] offset:36864
	ds_write_b128 v201, v[6:9]
	ds_write_b128 v202, v[2:5] offset:36864
	s_waitcnt lgkmcnt(0)
	s_barrier
	s_waitcnt vmcnt(0)
	v_cmp_lt_f32_e32 vcc, s38, v50
	s_nop 1
	v_cndmask_b32_e32 v52, 0, v234, vcc
	v_sub_f32_e32 v50, v52, v50
	v_exp_f32_e32 v50, v50
	s_and_b64 s[10:11], vcc, exec
	s_cselect_b32 s10, 0xffffffc0, 0
	s_add_i32 s28, s28, s33
	v_ldexp_f32 v63, v50, s10
	v_sub_f32_e32 v50, 1.0, v63
	s_cmp_ge_i32 s28, s13
	v_frexp_mant_f32_e32 v52, v50
	s_cselect_b64 s[10:11], -1, 0
	v_cmp_gt_f32_e64 s[70:71], s18, v52
	s_and_b64 vcc, exec, s[10:11]
	s_cbranch_vccnz .LBB0_743
	s_abs_i32 s36, s28
	s_mul_hi_u32 s37, s36, s3
	s_mul_i32 s38, s37, s12
	s_sub_i32 s36, s36, s38
	s_ashr_i32 s18, s28, 31
	s_add_i32 s38, s37, 1
	s_sub_i32 s39, s36, s12
	s_cmp_ge_u32 s36, s12
	s_cselect_b32 s37, s38, s37
	s_cselect_b32 s36, s39, s36
	s_add_i32 s38, s37, 1
	s_cmp_ge_u32 s36, s12
	s_cselect_b32 s36, s38, s37
	s_xor_b32 s36, s36, s18
	s_sub_i32 s37, s36, s18
	s_mul_i32 s18, s2, s37
	s_add_i32 s36, s28, s18
	v_readlane_b32 s38, v253, 26
	s_ashr_i32 s18, s37, 2
	s_add_i32 vcc_lo, s36, 2
	v_readlane_b32 s39, v253, 27
	s_and_b64 s[38:39], s[38:39], exec
	s_cselect_b32 s38, s36, vcc_lo
	s_cmp_gt_i32 s38, 1
	s_mov_b64 vcc, -1
	s_cbranch_scc0 .LBB0_740
	s_lshl_b32 s36, s18, 11
	s_lshl_b32 s39, s38, 7
	s_add_i32 s36, s36, s39
	s_addk_i32 s36, 0xff00
	s_mov_b64 vcc, 0

; DEVI unsigned cvt_pk_bf16(float lo, float hi) { unsigned r; asm volatile("v_cvt_pk_bf16_f32 %0, %1, %2" : "=v"(r) : "v"(lo), "v"(hi)); return r; }
; DEVI void unpack8(const u32x4 w, float (&v)[8]) { v[0] = bflo(w.x); v[1] = bfhi(w.x); v[2] = bflo(w.y); v[3] = bfhi(w.y); v[4] = bflo(w.z); v[5] = bfhi(w.z); v[6] = bflo(w.w); v[7] = bfhi(w.w); }
; DEVI void ph_ret_out(const int wv, const Params& p, int l, unsigned char* lds_raw) {
;     ...
;         if (cid >= 2) {
;             const float* cp = (const float*)(p.ws + OFF_RT) + (size_t)(((row0 + ii) & 2047) * 32 + fq * 8) * 2;
;             float x1[8], x2[8]; unpack8(__builtin_bit_cast(u32x4, Qf[0]), x1); unpack8(__builtin_bit_cast(u32x4, Qf[1]), x2);
;             float y1[8], y2[8];
; #pragma unroll
;             for (int q4 = 0; q4 < 4; ++q4) { const f32x4 cs = *(const f32x4*)(cp + 4 * q4);
;                 y1[2 * q4] = x1[2 * q4] * cs[0] - x2[2 * q4] * cs[1]; y2[2 * q4] = x1[2 * q4] * cs[1] + x2[2 * q4] * cs[0];
;                 y1[2 * q4 + 1] = x1[2 * q4 + 1] * cs[2] - x2[2 * q4 + 1] * cs[3]; y2[2 * q4 + 1] = x1[2 * q4 + 1] * cs[3] + x2[2 * q4 + 1] * cs[2]; }
;             Qf[0] = mk_frag(cvt_pk_bf16(y1[0], y1[1]), cvt_pk_bf16(y1[2], y1[3]), cvt_pk_bf16(y1[4], y1[5]), cvt_pk_bf16(y1[6], y1[7]));
;             Qf[1] = mk_frag(cvt_pk_bf16(y2[0], y2[1]), cvt_pk_bf16(y2[2], y2[3]), cvt_pk_bf16(y2[4], y2[5]), cvt_pk_bf16(y2[6], y2[7]));
;         }
.LBB0_745:
	s_andn2_b64 vcc, exec, s[70:71]
	v_add_u32_e32 v101, s30, v91
	s_cbranch_vccnz .LBB0_732
	v_lshlrev_b32_e32 v58, 6, v101
	s_mov_b32 s18, 0x1ffc0
	v_and_or_b32 v58, v58, s18, v95
	v_readlane_b32 s30, v252, 17
	v_lshlrev_b32_e32 v103, 2, v58
	v_readlane_b32 s31, v252, 18
	s_nop 4
	v_mov_b32_e32 v58, v116
	v_mov_b32_e32 v59, v117
	v_mov_b32_e32 v60, v118
	v_mov_b32_e32 v61, v119
	s_waitcnt lgkmcnt(1)
	v_lshlrev_b32_e32 v117, 16, v54
	s_waitcnt lgkmcnt(0)
	v_lshlrev_b32_e32 v116, 16, v50
	s_nop 0
	v_pk_mul_f32 v[118:119], v[112:113], v[116:117] op_sel:[0,1] op_sel_hi:[1,0]
	v_pk_mul_f32 v[112:113], v[112:113], v[116:117]
	v_sub_f32_e32 v103, v118, v119
	v_add_f32_e32 v118, v113, v112
	v_and_b32_e32 v113, 0xffff0000, v54
	v_and_b32_e32 v112, 0xffff0000, v50
	v_pk_mul_f32 v[116:117], v[114:115], v[112:113] op_sel:[0,1] op_sel_hi:[1,0]
	v_pk_mul_f32 v[112:113], v[114:115], v[112:113]
	v_sub_f32_e32 v116, v116, v117
	v_add_f32_e32 v117, v113, v112
	v_lshlrev_b32_e32 v113, 16, v55
	v_lshlrev_b32_e32 v112, 16, v51
	v_and_b32_e32 v55, 0xffff0000, v55
	v_and_b32_e32 v54, 0xffff0000, v51
	v_pk_mul_f32 v[114:115], v[108:109], v[112:113] op_sel:[0,1] op_sel_hi:[1,0]
	v_pk_mul_f32 v[108:109], v[108:109], v[112:113]
	v_pk_mul_f32 v[50:51], v[110:111], v[54:55] op_sel:[0,1] op_sel_hi:[1,0]
	v_add_f32_e32 v108, v109, v108
	v_sub_f32_e32 v109, v50, v51
	v_pk_mul_f32 v[50:51], v[110:111], v[54:55]
	v_sub_f32_e32 v114, v114, v115
	v_add_f32_e32 v110, v51, v50
	v_lshlrev_b32_e32 v51, 16, v56
	v_lshlrev_b32_e32 v50, 16, v52
	v_pk_mul_f32 v[54:55], v[104:105], v[50:51] op_sel:[0,1] op_sel_hi:[1,0]
	v_pk_mul_f32 v[50:51], v[104:105], v[50:51]
	v_sub_f32_e32 v111, v54, v55
	v_add_f32_e32 v104, v51, v50
	v_and_b32_e32 v51, 0xffff0000, v56
	v_and_b32_e32 v50, 0xffff0000, v52
	v_pk_mul_f32 v[54:55], v[106:107], v[50:51] op_sel:[0,1] op_sel_hi:[1,0]
	v_pk_mul_f32 v[50:51], v[106:107], v[50:51]
	v_sub_f32_e32 v56, v54, v55
	v_add_f32_e32 v105, v51, v50
	v_lshlrev_b32_e32 v51, 16, v53
	v_lshlrev_b32_e32 v50, 16, v57
	v_pk_mul_f32 v[54:55], v[58:59], v[50:51]
	v_pk_mul_f32 v[50:51], v[58:59], v[50:51] op_sel:[1,0] op_sel_hi:[0,1]
	v_add_f32_e32 v58, v50, v51
	v_and_b32_e32 v51, 0xffff0000, v53
	v_and_b32_e32 v50, 0xffff0000, v57
	v_pk_mul_f32 v[52:53], v[60:61], v[50:51]
	v_pk_mul_f32 v[50:51], v[60:61], v[50:51] op_sel:[1,0] op_sel_hi:[0,1]
	v_sub_f32_e32 v52, v52, v53
	v_add_f32_e32 v53, v50, v51
	v_sub_f32_e32 v106, v54, v55
	v_cvt_pk_bf16_f32 v54, v103, v116
	v_cvt_pk_bf16_f32 v55, v114, v109
	v_cvt_pk_bf16_f32 v56, v111, v56
	v_cvt_pk_bf16_f32 v57, v106, v52
	v_cvt_pk_bf16_f32 v50, v118, v117
	v_cvt_pk_bf16_f32 v51, v108, v110
	v_cvt_pk_bf16_f32 v52, v104, v105
	v_cvt_pk_bf16_f32 v53, v58, v53
	s_branch .LBB0_732

; __global__ void __launch_bounds__(NTHREADS) mega(Params p) {
;     extern __shared__ __attribute__((aligned(16))) unsigned char lds_raw[];
	.amdhsa_kernel _Z4mega6Params
		.amdhsa_group_segment_fixed_size 0
		.amdhsa_private_segment_fixed_size 0
		.amdhsa_kernarg_size 448
		.amdhsa_user_sgpr_count 2
		.amdhsa_user_sgpr_dispatch_ptr 0
		.amdhsa_user_sgpr_queue_ptr 0
		.amdhsa_user_sgpr_kernarg_segment_ptr 1
		.amdhsa_user_sgpr_dispatch_id 0
		.amdhsa_user_sgpr_kernarg_preload_length 0
		.amdhsa_user_sgpr_kernarg_preload_offset 0
		.amdhsa_user_sgpr_private_segment_size 0
		.amdhsa_uses_dynamic_stack 0
		.amdhsa_enable_private_segment 0
		.amdhsa_system_sgpr_workgroup_id_x 1
		.amdhsa_system_sgpr_workgroup_id_y 0
		.amdhsa_system_sgpr_workgroup_id_z 0
		.amdhsa_system_sgpr_workgroup_info 0
		.amdhsa_system_vgpr_workitem_id 2
		.amdhsa_next_free_vgpr 256
		.amdhsa_next_free_sgpr 102
		.amdhsa_accum_offset 256
		.amdhsa_reserve_vcc 1
		.amdhsa_float_round_mode_32 0
		.amdhsa_float_round_mode_16_64 0
		.amdhsa_float_denorm_mode_32 3
		.amdhsa_float_denorm_mode_16_64 3
		.amdhsa_dx10_clamp 1
		.amdhsa_ieee_mode 1
		.amdhsa_fp16_overflow 0
		.amdhsa_tg_split 0
		.amdhsa_exception_fp_ieee_invalid_op 0
		.amdhsa_exception_fp_denorm_src 0
		.amdhsa_exception_fp_ieee_div_zero 0
		.amdhsa_exception_fp_ieee_overflow 0
		.amdhsa_exception_fp_ieee_underflow 0
		.amdhsa_exception_fp_ieee_inexact 0
		.amdhsa_exception_int_div_zero 0
	.end_amdhsa_kernel

; __global__ void __launch_bounds__(NTHREADS) mega(Params p) {
;     extern __shared__ __attribute__((aligned(16))) unsigned char lds_raw[];
amdhsa.kernels:
  - .agpr_count:     0
    .args:
      - .offset:         0
        .size:           192
        .value_kind:     by_value
      - .offset:         192
        .size:           4
        .value_kind:     hidden_block_count_x
      - .offset:         196
        .size:           4
        .value_kind:     hidden_block_count_y
      - .offset:         200
        .size:           4
        .value_kind:     hidden_block_count_z
      - .offset:         204
        .size:           2
        .value_kind:     hidden_group_size_x
      - .offset:         206
        .size:           2
        .value_kind:     hidden_group_size_y
      - .offset:         208
        .size:           2
        .value_kind:     hidden_group_size_z
      - .offset:         210
        .size:           2
        .value_kind:     hidden_remainder_x
      - .offset:         212
        .size:           2
        .value_kind:     hidden_remainder_y
      - .offset:         214
        .size:           2
        .value_kind:     hidden_remainder_z
      - .offset:         232
        .size:           8
        .value_kind:     hidden_global_offset_x
      - .offset:         240
        .size:           8
        .value_kind:     hidden_global_offset_y
      - .offset:         248
        .size:           8
        .value_kind:     hidden_global_offset_z
      - .offset:         256
        .size:           2
        .value_kind:     hidden_grid_dims
      - .offset:         280
        .size:           8
        .value_kind:     hidden_multigrid_sync_arg
      - .offset:         312
        .size:           4
        .value_kind:     hidden_dynamic_lds_size
    .group_segment_fixed_size: 0
    .kernarg_segment_align: 8
    .kernarg_segment_size: 448
    .language:       OpenCL C
    .language_version:
      - 2
      - 0
    .max_flat_workgroup_size: 512
    .name:           _Z4mega6Params
    .private_segment_fixed_size: 0
    .sgpr_count:     108
    .sgpr_spill_count: 330
    .symbol:         _Z4mega6Params.kd
    .uniform_work_group_size: 1
    .uses_dynamic_stack: false
    .vgpr_count:     256
    .vgpr_spill_count: 0
    .wavefront_size: 64
